# P6 epilogue: eight row-sum loads issued as one batch at epilogue start (v235-242) instead of one load+vmcnt0 per 16-row block; on top of P5 epilogue ring
# speedup vs baseline: 1.0135x; 1.0043x over previous
; __device__ __forceinline__ unsigned cvt_pk_bf16(float lo, float hi) { unsigned r; asm volatile("v_cvt_pk_bf16_f32 %0, %1, %2" : "=v"(r) : "v"(lo), "v"(hi)); return r; }
;     __device__ __forceinline__ void operator()(const f32x4 (&acc)[2][2][4][2], const Unit& u, int wr, int wc, int fr, int fq) const {
;         const int row0 = u.pm * BM + wr * 64 + fr, col0 = u.pn * BM + wc * 32 + 8 * fq;
; #pragma unroll
;         for (int ai = 0; ai < 2; ++ai)
; #pragma unroll
;             for (int m = 0; m < 4; ++m) { const int row = row0 + ai * HALF + m * 16; const float rs = 1.0f / sqrtf(rowss[row] * (1.0f / 2048.0f) + 1e-6f); bf16_t* rowp = O + (size_t)row * 8192 + col0;
; #pragma unroll
;                 for (int bj = 0; bj < 2; ++bj) { f32x4 v0 = acc[ai][bj][m][0] * rs, v1 = acc[ai][bj][m][1] * rs;
; #pragma unroll
;                     for (int e = 0; e < 4; ++e) { const float a = fmaxf(v0[e], 0.f), b = fmaxf(v1[e], 0.f); v0[e] = a * a; v1[e] = b * b; }
;                     u32x4 w; w.x = cvt_pk_bf16(v0[0], v0[1]); w.y = cvt_pk_bf16(v0[2], v0[3]); w.z = cvt_pk_bf16(v1[0], v1[1]); w.w = cvt_pk_bf16(v1[2], v1[3]);
;                     *(u32x4*)(rowp + bj * HALF) = w; } }
.LBB0_827:
	v_lshl_add_u32 v150, s2, 8, v152
	v_ashrrev_i32_e32 v151, 31, v150
	v_lshl_add_u64 v[144:145], v[150:151], 2, s[10:11]
	global_load_dword v235, v[144:145], off
	global_load_dword v236, v[144:145], off offset:64
	global_load_dword v237, v[144:145], off offset:128
	global_load_dword v238, v[144:145], off offset:192
	global_load_dword v239, v[144:145], off offset:512
	global_load_dword v240, v[144:145], off offset:576
	global_load_dword v241, v[144:145], off offset:640
	global_load_dword v242, v[144:145], off offset:704
	v_lshl_or_b32 v146, s60, 8, v154
	v_ashrrev_i32_e32 v147, 31, v146
	v_lshlrev_b64 v[148:149], 1, v[146:147]
	v_lshlrev_b64 v[164:165], 14, v[150:151]
	v_or_b32_e32 v162, 16, v150
	s_waitcnt vmcnt(0)
	v_fmamk_f32 v146, v235, 0x3a000000, v160
	v_mul_f32_e32 v147, 0x4f800000, v146
	v_cmp_gt_f32_e32 vcc, s55, v146
	v_ashrrev_i32_e32 v163, 31, v162
	s_nop 0
	v_cndmask_b32_e32 v151, v146, v147, vcc
	v_sqrt_f32_e32 v166, v151
	v_lshl_add_u64 v[146:147], s[12:13], 0, v[164:165]
	v_lshl_add_u64 v[146:147], v[146:147], 0, v[148:149]
	v_lshl_add_u64 v[164:165], v[162:163], 2, s[10:11]
	v_add_u32_e32 v167, -1, v166
	v_add_u32_e32 v168, 1, v166
	v_fma_f32 v169, -v167, v166, v151
	v_fma_f32 v170, -v168, v166, v151
	v_cmp_ge_f32_e64 s[4:5], 0, v169
	s_nop 1
	v_cndmask_b32_e64 v166, v166, v167, s[4:5]
	v_cmp_lt_f32_e64 s[4:5], 0, v170
	s_nop 1
	v_cndmask_b32_e64 v166, v166, v168, s[4:5]
	v_mul_f32_e32 v167, 0x37800000, v166
	v_cndmask_b32_e32 v166, v166, v167, vcc
	v_cmp_class_f32_e32 vcc, v151, v161
	s_nop 1
	v_cndmask_b32_e32 v151, v166, v151, vcc
	v_div_scale_f32 v166, s[4:5], v151, v151, 1.0
	v_rcp_f32_e32 v167, v166
	v_div_scale_f32 v168, vcc, 1.0, v151, 1.0
	v_fma_f32 v169, -v166, v167, 1.0
	v_fmac_f32_e32 v167, v169, v167
	v_mul_f32_e32 v169, v168, v167
	v_fma_f32 v170, -v166, v169, v168
	v_fmac_f32_e32 v169, v170, v167
	v_fma_f32 v166, -v166, v169, v168
	v_div_fmas_f32 v166, v166, v167, v169
	v_div_fixup_f32 v166, v166, v151, 1.0
	v_pk_mul_f32 v[126:127], v[126:127], v[166:167] op_sel_hi:[1,0]
	v_pk_mul_f32 v[124:125], v[124:125], v[166:167] op_sel_hi:[1,0]
	v_pk_mul_f32 v[122:123], v[122:123], v[166:167] op_sel_hi:[1,0]
	v_pk_mul_f32 v[120:121], v[120:121], v[166:167] op_sel_hi:[1,0]
	v_pk_mul_f32 v[114:115], v[114:115], v[166:167] op_sel_hi:[1,0]
	v_pk_mul_f32 v[112:113], v[112:113], v[166:167] op_sel_hi:[1,0]
	v_pk_mul_f32 v[118:119], v[118:119], v[166:167] op_sel_hi:[1,0]
	v_pk_mul_f32 v[116:117], v[116:117], v[166:167] op_sel_hi:[1,0]
	v_max_f32_e32 v124, 0, v124
	v_max_f32_e32 v120, 0, v120
	v_max_f32_e32 v125, 0, v125
	v_max_f32_e32 v121, 0, v121
	v_max_f32_e32 v126, 0, v126
	v_max_f32_e32 v122, 0, v122
	v_max_f32_e32 v127, 0, v127
	v_max_f32_e32 v123, 0, v123
	v_max_f32_e32 v112, 0, v112
	v_max_f32_e32 v113, 0, v113
	v_max_f32_e32 v114, 0, v114
	v_max_f32_e32 v115, 0, v115
	v_max_f32_e32 v116, 0, v116
	v_max_f32_e32 v117, 0, v117
	v_max_f32_e32 v118, 0, v118
	v_max_f32_e32 v119, 0, v119
	v_mul_f32_e32 v124, v124, v124
	v_mul_f32_e32 v120, v120, v120
	v_mul_f32_e32 v125, v125, v125
	v_mul_f32_e32 v121, v121, v121
	v_mul_f32_e32 v126, v126, v126
	v_mul_f32_e32 v122, v122, v122
	v_mul_f32_e32 v127, v127, v127
	v_mul_f32_e32 v123, v123, v123
	v_mul_f32_e32 v151, v112, v112
	v_mul_f32_e32 v166, v113, v113
	v_mul_f32_e32 v167, v114, v114
	v_mul_f32_e32 v168, v115, v115
	v_cvt_pk_bf16_f32 v112, v124, v125
	v_cvt_pk_bf16_f32 v113, v126, v127
	v_cvt_pk_bf16_f32 v114, v120, v121
	v_cvt_pk_bf16_f32 v115, v122, v123
	v_mul_f32_e32 v116, v116, v116
	v_mul_f32_e32 v117, v117, v117
	v_mul_f32_e32 v118, v118, v118
	v_mul_f32_e32 v119, v119, v119
	global_store_dwordx4 v[146:147], v[112:115], off
	s_nop 1
	v_cvt_pk_bf16_f32 v112, v116, v117
	v_cvt_pk_bf16_f32 v113, v118, v119
	v_cvt_pk_bf16_f32 v114, v151, v166
	v_cvt_pk_bf16_f32 v115, v167, v168
	global_store_dwordx4 v[146:147], v[112:115], off offset:256
	s_nop 0
	s_nop 0
	v_or_b32_e32 v112, 32, v150
	v_ashrrev_i32_e32 v113, 31, v112
	v_lshl_add_u64 v[116:117], v[112:113], 2, s[10:11]
	s_nop 0
	v_fmamk_f32 v114, v236, 0x3a000000, v160
	v_mul_f32_e32 v115, 0x4f800000, v114
	v_cmp_gt_f32_e32 vcc, s55, v114
	s_nop 1
	v_cndmask_b32_e32 v118, v114, v115, vcc
	v_sqrt_f32_e32 v119, v118
	v_lshlrev_b64 v[114:115], 14, v[162:163]
	v_lshl_add_u64 v[114:115], s[12:13], 0, v[114:115]
	v_lshl_add_u64 v[114:115], v[114:115], 0, v[148:149]
	v_add_u32_e32 v120, -1, v119
	v_add_u32_e32 v121, 1, v119
	v_fma_f32 v122, -v120, v119, v118
	v_fma_f32 v123, -v121, v119, v118
	v_cmp_ge_f32_e64 s[4:5], 0, v122
	s_nop 1
	v_cndmask_b32_e64 v119, v119, v120, s[4:5]
	v_cmp_lt_f32_e64 s[4:5], 0, v123
	s_nop 1
	v_cndmask_b32_e64 v119, v119, v121, s[4:5]
	v_mul_f32_e32 v120, 0x37800000, v119
	v_cndmask_b32_e32 v119, v119, v120, vcc
	v_cmp_class_f32_e32 vcc, v118, v161
	s_nop 1
	v_cndmask_b32_e32 v118, v119, v118, vcc
	v_div_scale_f32 v119, s[4:5], v118, v118, 1.0
	v_rcp_f32_e32 v120, v119
	v_div_scale_f32 v121, vcc, 1.0, v118, 1.0
	v_fma_f32 v122, -v119, v120, 1.0
	v_fmac_f32_e32 v120, v122, v120
	v_mul_f32_e32 v122, v121, v120
	v_fma_f32 v123, -v119, v122, v121
	v_fmac_f32_e32 v122, v123, v120
	v_fma_f32 v119, -v119, v122, v121
	v_div_fmas_f32 v119, v119, v120, v122
	v_div_fixup_f32 v118, v119, v118, 1.0
	v_pk_mul_f32 v[110:111], v[110:111], v[118:119] op_sel_hi:[1,0]
	v_pk_mul_f32 v[108:109], v[108:109], v[118:119] op_sel_hi:[1,0]
	v_pk_mul_f32 v[106:107], v[106:107], v[118:119] op_sel_hi:[1,0]
	v_pk_mul_f32 v[104:105], v[104:105], v[118:119] op_sel_hi:[1,0]
	v_pk_mul_f32 v[98:99], v[98:99], v[118:119] op_sel_hi:[1,0]
	v_pk_mul_f32 v[96:97], v[96:97], v[118:119] op_sel_hi:[1,0]
; __device__ __forceinline__ unsigned cvt_pk_bf16(float lo, float hi) { unsigned r; asm volatile("v_cvt_pk_bf16_f32 %0, %1, %2" : "=v"(r) : "v"(lo), "v"(hi)); return r; }
;     __device__ __forceinline__ void operator()(const f32x4 (&acc)[2][2][4][2], const Unit& u, int wr, int wc, int fr, int fq) const {
;     ...
;             for (int m = 0; m < 4; ++m) { const int row = row0 + ai * HALF + m * 16; const float rs = 1.0f / sqrtf(rowss[row] * (1.0f / 2048.0f) + 1e-6f); bf16_t* rowp = O + (size_t)row * 8192 + col0;
; #pragma unroll
;                 for (int bj = 0; bj < 2; ++bj) { f32x4 v0 = acc[ai][bj][m][0] * rs, v1 = acc[ai][bj][m][1] * rs;
; #pragma unroll
;                     for (int e = 0; e < 4; ++e) { const float a = fmaxf(v0[e], 0.f), b = fmaxf(v1[e], 0.f); v0[e] = a * a; v1[e] = b * b; }
;                     u32x4 w; w.x = cvt_pk_bf16(v0[0], v0[1]); w.y = cvt_pk_bf16(v0[2], v0[3]); w.z = cvt_pk_bf16(v1[0], v1[1]); w.w = cvt_pk_bf16(v1[2], v1[3]);
;                     *(u32x4*)(rowp + bj * HALF) = w; } }
	v_pk_mul_f32 v[102:103], v[102:103], v[118:119] op_sel_hi:[1,0]
	v_pk_mul_f32 v[100:101], v[100:101], v[118:119] op_sel_hi:[1,0]
	v_max_f32_e32 v108, 0, v108
	v_max_f32_e32 v104, 0, v104
	v_max_f32_e32 v109, 0, v109
	v_max_f32_e32 v105, 0, v105
	v_max_f32_e32 v110, 0, v110
	v_max_f32_e32 v106, 0, v106
	v_max_f32_e32 v111, 0, v111
	v_max_f32_e32 v107, 0, v107
	v_max_f32_e32 v96, 0, v96
	v_max_f32_e32 v97, 0, v97
	v_max_f32_e32 v98, 0, v98
	v_max_f32_e32 v99, 0, v99
	v_max_f32_e32 v100, 0, v100
	v_max_f32_e32 v101, 0, v101
	v_max_f32_e32 v102, 0, v102
	v_max_f32_e32 v103, 0, v103
	v_mul_f32_e32 v108, v108, v108
	v_mul_f32_e32 v104, v104, v104
	v_mul_f32_e32 v109, v109, v109
	v_mul_f32_e32 v105, v105, v105
	v_mul_f32_e32 v110, v110, v110
	v_mul_f32_e32 v106, v106, v106
	v_mul_f32_e32 v111, v111, v111
	v_mul_f32_e32 v107, v107, v107
	v_mul_f32_e32 v118, v96, v96
	v_mul_f32_e32 v119, v97, v97
	v_mul_f32_e32 v120, v98, v98
	v_mul_f32_e32 v121, v99, v99
	v_cvt_pk_bf16_f32 v96, v108, v109
	v_cvt_pk_bf16_f32 v97, v110, v111
	v_cvt_pk_bf16_f32 v98, v104, v105
	v_cvt_pk_bf16_f32 v99, v106, v107
	v_mul_f32_e32 v100, v100, v100
	v_mul_f32_e32 v101, v101, v101
	v_mul_f32_e32 v102, v102, v102
	v_mul_f32_e32 v103, v103, v103
	global_store_dwordx4 v[114:115], v[96:99], off
	s_nop 1
	v_cvt_pk_bf16_f32 v96, v100, v101
	v_cvt_pk_bf16_f32 v97, v102, v103
	v_cvt_pk_bf16_f32 v98, v118, v119
	v_cvt_pk_bf16_f32 v99, v120, v121
	global_store_dwordx4 v[114:115], v[96:99], off offset:256
	s_nop 0
	s_nop 0
	v_or_b32_e32 v96, 48, v150
	v_ashrrev_i32_e32 v97, 31, v96
	v_lshl_add_u64 v[100:101], v[96:97], 2, s[10:11]
	s_nop 0
	v_fmamk_f32 v98, v237, 0x3a000000, v160
	v_mul_f32_e32 v99, 0x4f800000, v98
	v_cmp_gt_f32_e32 vcc, s55, v98
	s_nop 1
	v_cndmask_b32_e32 v102, v98, v99, vcc
	v_sqrt_f32_e32 v103, v102
	v_lshlrev_b64 v[98:99], 14, v[112:113]
	v_lshl_add_u64 v[98:99], s[12:13], 0, v[98:99]
	v_lshl_add_u64 v[98:99], v[98:99], 0, v[148:149]
	v_add_u32_e32 v104, -1, v103
	v_add_u32_e32 v105, 1, v103
	v_fma_f32 v106, -v104, v103, v102
	v_fma_f32 v107, -v105, v103, v102
	v_cmp_ge_f32_e64 s[4:5], 0, v106
	s_nop 1
	v_cndmask_b32_e64 v103, v103, v104, s[4:5]
	v_cmp_lt_f32_e64 s[4:5], 0, v107
	s_nop 1
	v_cndmask_b32_e64 v103, v103, v105, s[4:5]
	v_mul_f32_e32 v104, 0x37800000, v103
	v_cndmask_b32_e32 v103, v103, v104, vcc
	v_cmp_class_f32_e32 vcc, v102, v161
	s_nop 1
	v_cndmask_b32_e32 v102, v103, v102, vcc
	v_div_scale_f32 v103, s[4:5], v102, v102, 1.0
	v_rcp_f32_e32 v104, v103
	v_div_scale_f32 v105, vcc, 1.0, v102, 1.0
	v_fma_f32 v106, -v103, v104, 1.0
	v_fmac_f32_e32 v104, v106, v104
	v_mul_f32_e32 v106, v105, v104
	v_fma_f32 v107, -v103, v106, v105
	v_fmac_f32_e32 v106, v107, v104
	v_fma_f32 v103, -v103, v106, v105
	v_div_fmas_f32 v103, v103, v104, v106
	v_div_fixup_f32 v102, v103, v102, 1.0
	v_pk_mul_f32 v[94:95], v[94:95], v[102:103] op_sel_hi:[1,0]
	v_pk_mul_f32 v[92:93], v[92:93], v[102:103] op_sel_hi:[1,0]
	v_pk_mul_f32 v[90:91], v[90:91], v[102:103] op_sel_hi:[1,0]
	v_pk_mul_f32 v[88:89], v[88:89], v[102:103] op_sel_hi:[1,0]
	v_pk_mul_f32 v[82:83], v[82:83], v[102:103] op_sel_hi:[1,0]
	v_pk_mul_f32 v[80:81], v[80:81], v[102:103] op_sel_hi:[1,0]
	v_pk_mul_f32 v[86:87], v[86:87], v[102:103] op_sel_hi:[1,0]
	v_pk_mul_f32 v[84:85], v[84:85], v[102:103] op_sel_hi:[1,0]
	v_max_f32_e32 v92, 0, v92
	v_max_f32_e32 v88, 0, v88
	v_max_f32_e32 v93, 0, v93
	v_max_f32_e32 v89, 0, v89
	v_max_f32_e32 v94, 0, v94
	v_max_f32_e32 v90, 0, v90
	v_max_f32_e32 v95, 0, v95
	v_max_f32_e32 v91, 0, v91
	v_max_f32_e32 v80, 0, v80
	v_max_f32_e32 v81, 0, v81
	v_max_f32_e32 v82, 0, v82
	v_max_f32_e32 v83, 0, v83
	v_max_f32_e32 v84, 0, v84
	v_max_f32_e32 v85, 0, v85
	v_max_f32_e32 v86, 0, v86
	v_max_f32_e32 v87, 0, v87
	v_mul_f32_e32 v92, v92, v92
	v_mul_f32_e32 v88, v88, v88
	v_mul_f32_e32 v93, v93, v93
	v_mul_f32_e32 v89, v89, v89
	v_mul_f32_e32 v94, v94, v94
	v_mul_f32_e32 v90, v90, v90
	v_mul_f32_e32 v95, v95, v95
	v_mul_f32_e32 v91, v91, v91
	v_mul_f32_e32 v102, v80, v80
	v_mul_f32_e32 v103, v81, v81
	v_mul_f32_e32 v104, v82, v82
	v_mul_f32_e32 v105, v83, v83
	v_cvt_pk_bf16_f32 v80, v92, v93
	v_cvt_pk_bf16_f32 v81, v94, v95
	v_cvt_pk_bf16_f32 v82, v88, v89
	v_cvt_pk_bf16_f32 v83, v90, v91
	v_mul_f32_e32 v84, v84, v84
	v_mul_f32_e32 v85, v85, v85
	v_mul_f32_e32 v86, v86, v86
	v_mul_f32_e32 v87, v87, v87
	global_store_dwordx4 v[98:99], v[80:83], off
	s_nop 1
	v_cvt_pk_bf16_f32 v80, v84, v85
	v_cvt_pk_bf16_f32 v81, v86, v87
	v_cvt_pk_bf16_f32 v82, v102, v103
	v_cvt_pk_bf16_f32 v83, v104, v105
	global_store_dwordx4 v[98:99], v[80:83], off offset:256
	s_nop 0
	s_nop 0
	v_fmamk_f32 v80, v238, 0x3a000000, v160
	v_mul_f32_e32 v81, 0x4f800000, v80
	v_cmp_gt_f32_e32 vcc, s55, v80
	s_nop 1
	v_cndmask_b32_e32 v82, v80, v81, vcc
	v_sqrt_f32_e32 v83, v82
	v_lshlrev_b64 v[80:81], 14, v[96:97]
	v_lshl_add_u64 v[80:81], s[12:13], 0, v[80:81]
	v_lshl_add_u64 v[80:81], v[80:81], 0, v[148:149]
	v_add_u32_e32 v84, -1, v83
	v_add_u32_e32 v85, 1, v83
	v_fma_f32 v86, -v84, v83, v82
	v_fma_f32 v87, -v85, v83, v82
	v_cmp_ge_f32_e64 s[4:5], 0, v86
	s_nop 1
	v_cndmask_b32_e64 v83, v83, v84, s[4:5]
	v_cmp_lt_f32_e64 s[4:5], 0, v87
	s_nop 1
	v_cndmask_b32_e64 v83, v83, v85, s[4:5]
	v_mul_f32_e32 v84, 0x37800000, v83
	v_cndmask_b32_e32 v83, v83, v84, vcc
	v_cmp_class_f32_e32 vcc, v82, v161
	s_nop 1
	v_cndmask_b32_e32 v82, v83, v82, vcc
	v_div_scale_f32 v83, s[4:5], v82, v82, 1.0
	v_rcp_f32_e32 v84, v83
	v_div_scale_f32 v85, vcc, 1.0, v82, 1.0
	v_fma_f32 v86, -v83, v84, 1.0
	v_fmac_f32_e32 v84, v86, v84
	v_mul_f32_e32 v86, v85, v84
	v_fma_f32 v87, -v83, v86, v85
	v_fmac_f32_e32 v86, v87, v84
	v_fma_f32 v83, -v83, v86, v85
; __device__ __forceinline__ unsigned cvt_pk_bf16(float lo, float hi) { unsigned r; asm volatile("v_cvt_pk_bf16_f32 %0, %1, %2" : "=v"(r) : "v"(lo), "v"(hi)); return r; }
;     __device__ __forceinline__ void operator()(const f32x4 (&acc)[2][2][4][2], const Unit& u, int wr, int wc, int fr, int fq) const {
;     ...
;             for (int m = 0; m < 4; ++m) { const int row = row0 + ai * HALF + m * 16; const float rs = 1.0f / sqrtf(rowss[row] * (1.0f / 2048.0f) + 1e-6f); bf16_t* rowp = O + (size_t)row * 8192 + col0;
; #pragma unroll
;                 for (int bj = 0; bj < 2; ++bj) { f32x4 v0 = acc[ai][bj][m][0] * rs, v1 = acc[ai][bj][m][1] * rs;
; #pragma unroll
;                     for (int e = 0; e < 4; ++e) { const float a = fmaxf(v0[e], 0.f), b = fmaxf(v1[e], 0.f); v0[e] = a * a; v1[e] = b * b; }
;                     u32x4 w; w.x = cvt_pk_bf16(v0[0], v0[1]); w.y = cvt_pk_bf16(v0[2], v0[3]); w.z = cvt_pk_bf16(v1[0], v1[1]); w.w = cvt_pk_bf16(v1[2], v1[3]);
;                     *(u32x4*)(rowp + bj * HALF) = w; } }
	v_div_fmas_f32 v83, v83, v84, v86
	v_div_fixup_f32 v82, v83, v82, 1.0
	v_pk_mul_f32 v[78:79], v[78:79], v[82:83] op_sel_hi:[1,0]
	v_pk_mul_f32 v[76:77], v[76:77], v[82:83] op_sel_hi:[1,0]
	v_pk_mul_f32 v[74:75], v[74:75], v[82:83] op_sel_hi:[1,0]
	v_pk_mul_f32 v[72:73], v[72:73], v[82:83] op_sel_hi:[1,0]
	v_pk_mul_f32 v[66:67], v[66:67], v[82:83] op_sel_hi:[1,0]
	v_pk_mul_f32 v[64:65], v[64:65], v[82:83] op_sel_hi:[1,0]
	v_pk_mul_f32 v[70:71], v[70:71], v[82:83] op_sel_hi:[1,0]
	v_pk_mul_f32 v[68:69], v[68:69], v[82:83] op_sel_hi:[1,0]
	v_max_f32_e32 v76, 0, v76
	v_max_f32_e32 v72, 0, v72
	v_max_f32_e32 v77, 0, v77
	v_max_f32_e32 v73, 0, v73
	v_max_f32_e32 v78, 0, v78
	v_max_f32_e32 v74, 0, v74
	v_max_f32_e32 v79, 0, v79
	v_max_f32_e32 v75, 0, v75
	v_max_f32_e32 v64, 0, v64
	v_max_f32_e32 v65, 0, v65
	v_max_f32_e32 v66, 0, v66
	v_max_f32_e32 v67, 0, v67
	v_max_f32_e32 v68, 0, v68
	v_max_f32_e32 v69, 0, v69
	v_max_f32_e32 v70, 0, v70
	v_max_f32_e32 v71, 0, v71
	v_mul_f32_e32 v76, v76, v76
	v_mul_f32_e32 v72, v72, v72
	v_mul_f32_e32 v77, v77, v77
	v_mul_f32_e32 v73, v73, v73
	v_mul_f32_e32 v78, v78, v78
	v_mul_f32_e32 v74, v74, v74
	v_mul_f32_e32 v79, v79, v79
	v_mul_f32_e32 v75, v75, v75
	v_mul_f32_e32 v82, v64, v64
	v_mul_f32_e32 v83, v65, v65
	v_mul_f32_e32 v84, v66, v66
	v_mul_f32_e32 v85, v67, v67
	v_cvt_pk_bf16_f32 v64, v76, v77
	v_cvt_pk_bf16_f32 v65, v78, v79
	v_cvt_pk_bf16_f32 v66, v72, v73
	v_cvt_pk_bf16_f32 v67, v74, v75
	v_mul_f32_e32 v68, v68, v68
	v_mul_f32_e32 v69, v69, v69
	v_mul_f32_e32 v70, v70, v70
	v_mul_f32_e32 v71, v71, v71
	global_store_dwordx4 v[80:81], v[64:67], off
	s_nop 1
	v_cvt_pk_bf16_f32 v64, v68, v69
	v_cvt_pk_bf16_f32 v65, v70, v71
	v_cvt_pk_bf16_f32 v66, v82, v83
	v_cvt_pk_bf16_f32 v67, v84, v85
	global_store_dwordx4 v[80:81], v[64:67], off offset:256
	s_nop 0
	s_nop 0
	v_fmamk_f32 v64, v239, 0x3a000000, v160
	v_mul_f32_e32 v65, 0x4f800000, v64
	v_cmp_gt_f32_e32 vcc, s55, v64
	s_nop 1
	v_cndmask_b32_e32 v66, v64, v65, vcc
	v_sqrt_f32_e32 v67, v66
	v_lshl_add_u64 v[64:65], v[146:147], 0, s[18:19]
	v_add_u32_e32 v68, -1, v67
	v_add_u32_e32 v69, 1, v67
	v_fma_f32 v70, -v68, v67, v66
	v_fma_f32 v71, -v69, v67, v66
	v_cmp_ge_f32_e64 s[4:5], 0, v70
	s_nop 1
	v_cndmask_b32_e64 v67, v67, v68, s[4:5]
	v_cmp_lt_f32_e64 s[4:5], 0, v71
	s_nop 1
	v_cndmask_b32_e64 v67, v67, v69, s[4:5]
	v_mul_f32_e32 v68, 0x37800000, v67
	v_cndmask_b32_e32 v67, v67, v68, vcc
	v_cmp_class_f32_e32 vcc, v66, v161
	s_nop 1
	v_cndmask_b32_e32 v68, v67, v66, vcc
	v_div_scale_f32 v69, s[4:5], v68, v68, 1.0
	v_rcp_f32_e32 v70, v69
	v_add_co_u32_e32 v66, vcc, s56, v146
	v_fma_f32 v72, -v69, v70, 1.0
	s_nop 0
	v_addc_co_u32_e32 v67, vcc, 0, v147, vcc
	v_div_scale_f32 v71, vcc, 1.0, v68, 1.0
	v_fmac_f32_e32 v70, v72, v70
	v_mul_f32_e32 v72, v71, v70
	v_fma_f32 v73, -v69, v72, v71
	v_fmac_f32_e32 v72, v73, v70
	v_fma_f32 v69, -v69, v72, v71
	v_div_fmas_f32 v69, v69, v70, v72
	v_div_fixup_f32 v68, v69, v68, 1.0
	v_pk_mul_f32 v[62:63], v[62:63], v[68:69] op_sel_hi:[1,0]
	v_pk_mul_f32 v[60:61], v[60:61], v[68:69] op_sel_hi:[1,0]
	v_pk_mul_f32 v[58:59], v[58:59], v[68:69] op_sel_hi:[1,0]
	v_pk_mul_f32 v[56:57], v[56:57], v[68:69] op_sel_hi:[1,0]
	v_pk_mul_f32 v[50:51], v[50:51], v[68:69] op_sel_hi:[1,0]
	v_pk_mul_f32 v[48:49], v[48:49], v[68:69] op_sel_hi:[1,0]
	v_pk_mul_f32 v[54:55], v[54:55], v[68:69] op_sel_hi:[1,0]
	v_pk_mul_f32 v[52:53], v[52:53], v[68:69] op_sel_hi:[1,0]
	v_max_f32_e32 v60, 0, v60
	v_max_f32_e32 v56, 0, v56
	v_max_f32_e32 v61, 0, v61
	v_max_f32_e32 v57, 0, v57
	v_max_f32_e32 v62, 0, v62
	v_max_f32_e32 v58, 0, v58
	v_max_f32_e32 v63, 0, v63
	v_max_f32_e32 v59, 0, v59
	v_max_f32_e32 v48, 0, v48
	v_max_f32_e32 v49, 0, v49
	v_max_f32_e32 v50, 0, v50
	v_max_f32_e32 v51, 0, v51
	v_max_f32_e32 v52, 0, v52
	v_max_f32_e32 v53, 0, v53
	v_max_f32_e32 v54, 0, v54
	v_max_f32_e32 v55, 0, v55
	v_mul_f32_e32 v60, v60, v60
	v_mul_f32_e32 v56, v56, v56
	v_mul_f32_e32 v61, v61, v61
	v_mul_f32_e32 v57, v57, v57
	v_mul_f32_e32 v62, v62, v62
	v_mul_f32_e32 v58, v58, v58
	v_mul_f32_e32 v63, v63, v63
	v_mul_f32_e32 v59, v59, v59
	v_mul_f32_e32 v68, v48, v48
	v_mul_f32_e32 v69, v49, v49
	v_mul_f32_e32 v70, v50, v50
	v_mul_f32_e32 v71, v51, v51
	v_cvt_pk_bf16_f32 v48, v60, v61
	v_cvt_pk_bf16_f32 v49, v62, v63
	v_cvt_pk_bf16_f32 v50, v56, v57
	v_cvt_pk_bf16_f32 v51, v58, v59
	v_mul_f32_e32 v52, v52, v52
	v_mul_f32_e32 v53, v53, v53
	v_mul_f32_e32 v54, v54, v54
	v_mul_f32_e32 v55, v55, v55
	global_store_dwordx4 v[66:67], v[48:51], off
	s_nop 1
	v_cvt_pk_bf16_f32 v48, v52, v53
	v_cvt_pk_bf16_f32 v49, v54, v55
	v_cvt_pk_bf16_f32 v50, v68, v69
	v_cvt_pk_bf16_f32 v51, v70, v71
	global_store_dwordx4 v[64:65], v[48:51], off offset:256
	s_nop 0
	s_nop 0
	v_fmamk_f32 v48, v240, 0x3a000000, v160
	v_mul_f32_e32 v49, 0x4f800000, v48
	v_cmp_gt_f32_e32 vcc, s55, v48
	s_nop 1
	v_cndmask_b32_e32 v50, v48, v49, vcc
	v_sqrt_f32_e32 v51, v50
	v_lshl_add_u64 v[48:49], v[146:147], 0, s[20:21]
	v_add_u32_e32 v52, -1, v51
	v_add_u32_e32 v53, 1, v51
	v_fma_f32 v54, -v52, v51, v50
	v_fma_f32 v55, -v53, v51, v50
	v_cmp_ge_f32_e64 s[4:5], 0, v54
	s_nop 1
	v_cndmask_b32_e64 v51, v51, v52, s[4:5]
	v_cmp_lt_f32_e64 s[4:5], 0, v55
	s_nop 1
	v_cndmask_b32_e64 v51, v51, v53, s[4:5]
	v_mul_f32_e32 v52, 0x37800000, v51
	v_cndmask_b32_e32 v51, v51, v52, vcc
	v_cmp_class_f32_e32 vcc, v50, v161
	s_nop 1
	v_cndmask_b32_e32 v52, v51, v50, vcc
	v_div_scale_f32 v53, s[4:5], v52, v52, 1.0
	v_rcp_f32_e32 v54, v53
	v_add_co_u32_e32 v50, vcc, s57, v146
	v_fma_f32 v56, -v53, v54, 1.0
	s_nop 0
	v_addc_co_u32_e32 v51, vcc, 0, v147, vcc
	v_div_scale_f32 v55, vcc, 1.0, v52, 1.0
	v_fmac_f32_e32 v54, v56, v54
; __device__ __forceinline__ unsigned cvt_pk_bf16(float lo, float hi) { unsigned r; asm volatile("v_cvt_pk_bf16_f32 %0, %1, %2" : "=v"(r) : "v"(lo), "v"(hi)); return r; }
;     __device__ __forceinline__ void operator()(const f32x4 (&acc)[2][2][4][2], const Unit& u, int wr, int wc, int fr, int fq) const {
;     ...
;             for (int m = 0; m < 4; ++m) { const int row = row0 + ai * HALF + m * 16; const float rs = 1.0f / sqrtf(rowss[row] * (1.0f / 2048.0f) + 1e-6f); bf16_t* rowp = O + (size_t)row * 8192 + col0;
; #pragma unroll
;                 for (int bj = 0; bj < 2; ++bj) { f32x4 v0 = acc[ai][bj][m][0] * rs, v1 = acc[ai][bj][m][1] * rs;
; #pragma unroll
;                     for (int e = 0; e < 4; ++e) { const float a = fmaxf(v0[e], 0.f), b = fmaxf(v1[e], 0.f); v0[e] = a * a; v1[e] = b * b; }
;                     u32x4 w; w.x = cvt_pk_bf16(v0[0], v0[1]); w.y = cvt_pk_bf16(v0[2], v0[3]); w.z = cvt_pk_bf16(v1[0], v1[1]); w.w = cvt_pk_bf16(v1[2], v1[3]);
;                     *(u32x4*)(rowp + bj * HALF) = w; } }
	v_mul_f32_e32 v56, v55, v54
	v_fma_f32 v57, -v53, v56, v55
	v_fmac_f32_e32 v56, v57, v54
	v_fma_f32 v53, -v53, v56, v55
	v_div_fmas_f32 v53, v53, v54, v56
	v_div_fixup_f32 v52, v53, v52, 1.0
	v_pk_mul_f32 v[46:47], v[46:47], v[52:53] op_sel_hi:[1,0]
	v_pk_mul_f32 v[44:45], v[44:45], v[52:53] op_sel_hi:[1,0]
	v_pk_mul_f32 v[42:43], v[42:43], v[52:53] op_sel_hi:[1,0]
	v_pk_mul_f32 v[40:41], v[40:41], v[52:53] op_sel_hi:[1,0]
	v_pk_mul_f32 v[34:35], v[34:35], v[52:53] op_sel_hi:[1,0]
	v_pk_mul_f32 v[32:33], v[32:33], v[52:53] op_sel_hi:[1,0]
	v_pk_mul_f32 v[38:39], v[38:39], v[52:53] op_sel_hi:[1,0]
	v_pk_mul_f32 v[36:37], v[36:37], v[52:53] op_sel_hi:[1,0]
	v_max_f32_e32 v44, 0, v44
	v_max_f32_e32 v40, 0, v40
	v_max_f32_e32 v45, 0, v45
	v_max_f32_e32 v41, 0, v41
	v_max_f32_e32 v46, 0, v46
	v_max_f32_e32 v42, 0, v42
	v_max_f32_e32 v47, 0, v47
	v_max_f32_e32 v43, 0, v43
	v_max_f32_e32 v32, 0, v32
	v_max_f32_e32 v33, 0, v33
	v_max_f32_e32 v34, 0, v34
	v_max_f32_e32 v35, 0, v35
	v_max_f32_e32 v36, 0, v36
	v_max_f32_e32 v37, 0, v37
	v_max_f32_e32 v38, 0, v38
	v_max_f32_e32 v39, 0, v39
	v_mul_f32_e32 v44, v44, v44
	v_mul_f32_e32 v40, v40, v40
	v_mul_f32_e32 v45, v45, v45
	v_mul_f32_e32 v41, v41, v41
	v_mul_f32_e32 v46, v46, v46
	v_mul_f32_e32 v42, v42, v42
	v_mul_f32_e32 v47, v47, v47
	v_mul_f32_e32 v43, v43, v43
	v_mul_f32_e32 v52, v32, v32
	v_mul_f32_e32 v53, v33, v33
	v_mul_f32_e32 v54, v34, v34
	v_mul_f32_e32 v55, v35, v35
	v_cvt_pk_bf16_f32 v32, v44, v45
	v_cvt_pk_bf16_f32 v33, v46, v47
	v_cvt_pk_bf16_f32 v34, v40, v41
	v_cvt_pk_bf16_f32 v35, v42, v43
	v_mul_f32_e32 v36, v36, v36
	v_mul_f32_e32 v37, v37, v37
	v_mul_f32_e32 v38, v38, v38
	v_mul_f32_e32 v39, v39, v39
	global_store_dwordx4 v[50:51], v[32:35], off
	s_nop 1
	v_cvt_pk_bf16_f32 v32, v36, v37
	v_cvt_pk_bf16_f32 v33, v38, v39
	v_cvt_pk_bf16_f32 v34, v52, v53
	v_cvt_pk_bf16_f32 v35, v54, v55
	global_store_dwordx4 v[48:49], v[32:35], off offset:256
	s_nop 0
	s_nop 0
	v_fmamk_f32 v32, v241, 0x3a000000, v160
	v_mul_f32_e32 v33, 0x4f800000, v32
	v_cmp_gt_f32_e32 vcc, s55, v32
	s_nop 1
	v_cndmask_b32_e32 v34, v32, v33, vcc
	v_sqrt_f32_e32 v35, v34
	v_lshl_add_u64 v[32:33], v[146:147], 0, s[22:23]
	v_add_u32_e32 v36, -1, v35
	v_add_u32_e32 v37, 1, v35
	v_fma_f32 v38, -v36, v35, v34
	v_fma_f32 v39, -v37, v35, v34
	v_cmp_ge_f32_e64 s[4:5], 0, v38
	s_nop 1
	v_cndmask_b32_e64 v35, v35, v36, s[4:5]
	v_cmp_lt_f32_e64 s[4:5], 0, v39
	s_nop 1
	v_cndmask_b32_e64 v35, v35, v37, s[4:5]
	v_mul_f32_e32 v36, 0x37800000, v35
	v_cndmask_b32_e32 v35, v35, v36, vcc
	v_cmp_class_f32_e32 vcc, v34, v161
	s_nop 1
	v_cndmask_b32_e32 v36, v35, v34, vcc
	v_div_scale_f32 v37, s[4:5], v36, v36, 1.0
	v_rcp_f32_e32 v38, v37
	v_add_co_u32_e32 v34, vcc, s58, v146
	v_fma_f32 v40, -v37, v38, 1.0
	s_nop 0
	v_addc_co_u32_e32 v35, vcc, 0, v147, vcc
	v_div_scale_f32 v39, vcc, 1.0, v36, 1.0
	v_fmac_f32_e32 v38, v40, v38
	v_mul_f32_e32 v40, v39, v38
	v_fma_f32 v41, -v37, v40, v39
	v_fmac_f32_e32 v40, v41, v38
	v_fma_f32 v37, -v37, v40, v39
	v_div_fmas_f32 v37, v37, v38, v40
	v_div_fixup_f32 v36, v37, v36, 1.0
	v_pk_mul_f32 v[30:31], v[30:31], v[36:37] op_sel_hi:[1,0]
	v_pk_mul_f32 v[28:29], v[28:29], v[36:37] op_sel_hi:[1,0]
	v_pk_mul_f32 v[26:27], v[26:27], v[36:37] op_sel_hi:[1,0]
	v_pk_mul_f32 v[24:25], v[24:25], v[36:37] op_sel_hi:[1,0]
	v_pk_mul_f32 v[18:19], v[18:19], v[36:37] op_sel_hi:[1,0]
	v_pk_mul_f32 v[16:17], v[16:17], v[36:37] op_sel_hi:[1,0]
	v_pk_mul_f32 v[22:23], v[22:23], v[36:37] op_sel_hi:[1,0]
	v_pk_mul_f32 v[20:21], v[20:21], v[36:37] op_sel_hi:[1,0]
	v_max_f32_e32 v28, 0, v28
	v_max_f32_e32 v24, 0, v24
	v_max_f32_e32 v29, 0, v29
	v_max_f32_e32 v25, 0, v25
	v_max_f32_e32 v30, 0, v30
	v_max_f32_e32 v26, 0, v26
	v_max_f32_e32 v31, 0, v31
	v_max_f32_e32 v27, 0, v27
	v_max_f32_e32 v16, 0, v16
	v_max_f32_e32 v17, 0, v17
	v_max_f32_e32 v18, 0, v18
	v_max_f32_e32 v19, 0, v19
	v_max_f32_e32 v20, 0, v20
; __device__ __forceinline__ unsigned cvt_pk_bf16(float lo, float hi) { unsigned r; asm volatile("v_cvt_pk_bf16_f32 %0, %1, %2" : "=v"(r) : "v"(lo), "v"(hi)); return r; }
;     __device__ __forceinline__ void operator()(const f32x4 (&acc)[2][2][4][2], const Unit& u, int wr, int wc, int fr, int fq) const {
;     ...
;             for (int m = 0; m < 4; ++m) { const int row = row0 + ai * HALF + m * 16; const float rs = 1.0f / sqrtf(rowss[row] * (1.0f / 2048.0f) + 1e-6f); bf16_t* rowp = O + (size_t)row * 8192 + col0;
; #pragma unroll
;                 for (int bj = 0; bj < 2; ++bj) { f32x4 v0 = acc[ai][bj][m][0] * rs, v1 = acc[ai][bj][m][1] * rs;
; #pragma unroll
;                     for (int e = 0; e < 4; ++e) { const float a = fmaxf(v0[e], 0.f), b = fmaxf(v1[e], 0.f); v0[e] = a * a; v1[e] = b * b; }
;                     u32x4 w; w.x = cvt_pk_bf16(v0[0], v0[1]); w.y = cvt_pk_bf16(v0[2], v0[3]); w.z = cvt_pk_bf16(v1[0], v1[1]); w.w = cvt_pk_bf16(v1[2], v1[3]);
;                     *(u32x4*)(rowp + bj * HALF) = w; } }
	v_max_f32_e32 v21, 0, v21
	v_max_f32_e32 v22, 0, v22
	v_max_f32_e32 v23, 0, v23
	v_mul_f32_e32 v28, v28, v28
	v_mul_f32_e32 v24, v24, v24
	v_mul_f32_e32 v29, v29, v29
	v_mul_f32_e32 v25, v25, v25
	v_mul_f32_e32 v30, v30, v30
	v_mul_f32_e32 v26, v26, v26
	v_mul_f32_e32 v31, v31, v31
	v_mul_f32_e32 v27, v27, v27
	v_mul_f32_e32 v36, v16, v16
	v_mul_f32_e32 v37, v17, v17
	v_mul_f32_e32 v38, v18, v18
	v_mul_f32_e32 v39, v19, v19
	v_cvt_pk_bf16_f32 v16, v28, v29
	v_cvt_pk_bf16_f32 v17, v30, v31
	v_cvt_pk_bf16_f32 v18, v24, v25
	v_cvt_pk_bf16_f32 v19, v26, v27
	v_mul_f32_e32 v20, v20, v20
	v_mul_f32_e32 v21, v21, v21
	v_mul_f32_e32 v22, v22, v22
	v_mul_f32_e32 v23, v23, v23
	global_store_dwordx4 v[34:35], v[16:19], off
	s_nop 1
	v_cvt_pk_bf16_f32 v16, v20, v21
	v_cvt_pk_bf16_f32 v17, v22, v23
	v_cvt_pk_bf16_f32 v18, v36, v37
	v_cvt_pk_bf16_f32 v19, v38, v39
	global_store_dwordx4 v[32:33], v[16:19], off offset:256
	s_nop 0
	s_nop 0
	v_fmamk_f32 v16, v242, 0x3a000000, v160
	v_mul_f32_e32 v17, 0x4f800000, v16
	v_cmp_gt_f32_e32 vcc, s55, v16
	s_nop 1
	v_cndmask_b32_e32 v18, v16, v17, vcc
	v_sqrt_f32_e32 v19, v18
	v_lshl_add_u64 v[16:17], v[146:147], 0, s[24:25]
	v_add_u32_e32 v20, -1, v19
	v_add_u32_e32 v21, 1, v19
	v_fma_f32 v22, -v20, v19, v18
	v_fma_f32 v23, -v21, v19, v18
	v_cmp_ge_f32_e64 s[4:5], 0, v22
	s_nop 1
	v_cndmask_b32_e64 v19, v19, v20, s[4:5]
	v_cmp_lt_f32_e64 s[4:5], 0, v23
	s_nop 1
	v_cndmask_b32_e64 v19, v19, v21, s[4:5]
	v_mul_f32_e32 v20, 0x37800000, v19
	v_cndmask_b32_e32 v19, v19, v20, vcc
	v_cmp_class_f32_e32 vcc, v18, v161
	s_nop 1
	v_cndmask_b32_e32 v20, v19, v18, vcc
	v_div_scale_f32 v21, s[4:5], v20, v20, 1.0
	v_rcp_f32_e32 v22, v21
	v_add_co_u32_e32 v18, vcc, s59, v146
	v_fma_f32 v24, -v21, v22, 1.0
	s_nop 0
	v_addc_co_u32_e32 v19, vcc, 0, v147, vcc
	v_div_scale_f32 v23, vcc, 1.0, v20, 1.0
	v_fmac_f32_e32 v22, v24, v22
	v_mul_f32_e32 v24, v23, v22
	v_fma_f32 v25, -v21, v24, v23
	v_fmac_f32_e32 v24, v25, v22
	v_fma_f32 v21, -v21, v24, v23
	v_div_fmas_f32 v21, v21, v22, v24
	v_div_fixup_f32 v20, v21, v20, 1.0
	v_pk_mul_f32 v[14:15], v[14:15], v[20:21] op_sel_hi:[1,0]
	v_pk_mul_f32 v[12:13], v[12:13], v[20:21] op_sel_hi:[1,0]
	v_pk_mul_f32 v[10:11], v[10:11], v[20:21] op_sel_hi:[1,0]
	v_pk_mul_f32 v[8:9], v[8:9], v[20:21] op_sel_hi:[1,0]
	v_pk_mul_f32 v[2:3], v[2:3], v[20:21] op_sel_hi:[1,0]
	v_pk_mul_f32 v[0:1], v[0:1], v[20:21] op_sel_hi:[1,0]
	v_pk_mul_f32 v[6:7], v[6:7], v[20:21] op_sel_hi:[1,0]
	v_pk_mul_f32 v[4:5], v[4:5], v[20:21] op_sel_hi:[1,0]
	v_max_f32_e32 v12, 0, v12
	v_max_f32_e32 v8, 0, v8
	v_max_f32_e32 v13, 0, v13
	v_max_f32_e32 v9, 0, v9
	v_max_f32_e32 v14, 0, v14
	v_max_f32_e32 v10, 0, v10
	v_max_f32_e32 v15, 0, v15
	v_max_f32_e32 v11, 0, v11
	v_max_f32_e32 v0, 0, v0
	v_max_f32_e32 v1, 0, v1
	v_max_f32_e32 v2, 0, v2
	v_max_f32_e32 v3, 0, v3
	s_andn2_b64 vcc, exec, s[0:1]
	v_max_f32_e32 v4, 0, v4
	v_max_f32_e32 v5, 0, v5
	v_max_f32_e32 v6, 0, v6
	v_max_f32_e32 v7, 0, v7
	v_mul_f32_e32 v12, v12, v12
	v_mul_f32_e32 v8, v8, v8
	v_mul_f32_e32 v13, v13, v13
	v_mul_f32_e32 v9, v9, v9
	v_mul_f32_e32 v14, v14, v14
	v_mul_f32_e32 v10, v10, v10
	v_mul_f32_e32 v15, v15, v15
	v_mul_f32_e32 v11, v11, v11
	v_mul_f32_e32 v20, v0, v0
	v_mul_f32_e32 v21, v1, v1
	v_mul_f32_e32 v22, v2, v2
	v_mul_f32_e32 v23, v3, v3
	v_cvt_pk_bf16_f32 v0, v12, v13
	v_cvt_pk_bf16_f32 v1, v14, v15
	v_cvt_pk_bf16_f32 v2, v8, v9
	v_cvt_pk_bf16_f32 v3, v10, v11
	s_mov_b64 s[0:1], -1
	v_mul_f32_e32 v4, v4, v4
	v_mul_f32_e32 v5, v5, v5
	v_mul_f32_e32 v6, v6, v6
	v_mul_f32_e32 v7, v7, v7
	global_store_dwordx4 v[18:19], v[0:3], off
	s_nop 1
	v_cvt_pk_bf16_f32 v0, v4, v5
	v_cvt_pk_bf16_f32 v1, v6, v7
	v_cvt_pk_bf16_f32 v2, v20, v21
	v_cvt_pk_bf16_f32 v3, v22, v23
	global_store_dwordx4 v[16:17], v[0:3], off offset:256
	s_cbranch_vccnz .LBB0_816
	s_andn2_b64 vcc, exec, s[8:9]
	s_cbranch_vccnz .LBB0_815
	s_barrier
	s_branch .LBB0_815

; __global__ void __launch_bounds__(NWAVES * 64, 2) mega(Args args) {
	.amdhsa_kernel _Z4mega4Args
		.amdhsa_group_segment_fixed_size 0
		.amdhsa_private_segment_fixed_size 0
		.amdhsa_kernarg_size 416
		.amdhsa_user_sgpr_count 2
		.amdhsa_user_sgpr_dispatch_ptr 0
		.amdhsa_user_sgpr_queue_ptr 0
		.amdhsa_user_sgpr_kernarg_segment_ptr 1
		.amdhsa_user_sgpr_dispatch_id 0
		.amdhsa_user_sgpr_kernarg_preload_length 0
		.amdhsa_user_sgpr_kernarg_preload_offset 0
		.amdhsa_user_sgpr_private_segment_size 0
		.amdhsa_uses_dynamic_stack 0
		.amdhsa_enable_private_segment 0
		.amdhsa_system_sgpr_workgroup_id_x 1
		.amdhsa_system_sgpr_workgroup_id_y 0
		.amdhsa_system_sgpr_workgroup_id_z 0
		.amdhsa_system_sgpr_workgroup_info 0
		.amdhsa_system_vgpr_workitem_id 2
		.amdhsa_next_free_vgpr 243
		.amdhsa_next_free_sgpr 98
		.amdhsa_accum_offset 244
		.amdhsa_reserve_vcc 1
		.amdhsa_float_round_mode_32 0
		.amdhsa_float_round_mode_16_64 0
		.amdhsa_float_denorm_mode_32 3
		.amdhsa_float_denorm_mode_16_64 3
		.amdhsa_dx10_clamp 1
		.amdhsa_ieee_mode 1
		.amdhsa_fp16_overflow 0
		.amdhsa_tg_split 0
		.amdhsa_exception_fp_ieee_invalid_op 0
		.amdhsa_exception_fp_denorm_src 0
		.amdhsa_exception_fp_ieee_div_zero 0
		.amdhsa_exception_fp_ieee_overflow 0
		.amdhsa_exception_fp_ieee_underflow 0
		.amdhsa_exception_fp_ieee_inexact 0
		.amdhsa_exception_int_div_zero 0
	.end_amdhsa_kernel

; __global__ void __launch_bounds__(NWAVES * 64, 2) mega(Args args) {
amdhsa.kernels:
  - .agpr_count:     0
    .args:
      - .offset:         0
        .size:           160
        .value_kind:     by_value
      - .offset:         160
        .size:           4
        .value_kind:     hidden_block_count_x
      - .offset:         164
        .size:           4
        .value_kind:     hidden_block_count_y
      - .offset:         168
        .size:           4
        .value_kind:     hidden_block_count_z
      - .offset:         172
        .size:           2
        .value_kind:     hidden_group_size_x
      - .offset:         174
        .size:           2
        .value_kind:     hidden_group_size_y
      - .offset:         176
        .size:           2
        .value_kind:     hidden_group_size_z
      - .offset:         178
        .size:           2
        .value_kind:     hidden_remainder_x
      - .offset:         180
        .size:           2
        .value_kind:     hidden_remainder_y
      - .offset:         182
        .size:           2
        .value_kind:     hidden_remainder_z
      - .offset:         200
        .size:           8
        .value_kind:     hidden_global_offset_x
      - .offset:         208
        .size:           8
        .value_kind:     hidden_global_offset_y
      - .offset:         216
        .size:           8
        .value_kind:     hidden_global_offset_z
      - .offset:         224
        .size:           2
        .value_kind:     hidden_grid_dims
      - .offset:         248
        .size:           8
        .value_kind:     hidden_multigrid_sync_arg
      - .offset:         280
        .size:           4
        .value_kind:     hidden_dynamic_lds_size
    .group_segment_fixed_size: 0
    .kernarg_segment_align: 8
    .kernarg_segment_size: 416
    .language:       OpenCL C
    .language_version:
      - 2
      - 0
    .max_flat_workgroup_size: 512
    .name:           _Z4mega4Args
    .private_segment_fixed_size: 0
    .sgpr_count:     104
    .sgpr_spill_count: 78
    .symbol:         _Z4mega4Args.kd
    .uniform_work_group_size: 1
    .uses_dynamic_stack: false
    .vgpr_count:     243
    .vgpr_spill_count: 0
    .wavefront_size: 64
